# p4team + P4 item loop hand-written: all 52 loads of an item in one batch (one exposed round trip per item instead of two), norm weights loaded into dead S_n fragment registers
# speedup vs baseline: 1.0050x; 1.0050x over previous
; #define GAS __attribute__((address_space(1)))
; __device__ __forceinline__ void p4_load_a(P4Pre& P, const P4Ptr& p, int lane) {
;     const int r = lane & 15, g = lane >> 4, t = 16 * p.mt + r;
; #pragma unroll
;     for (int kb = 0; kb < 4; ++kb) P.ya[kb] = *(const GAS bf16x8*)(p.region + (size_t)((p.mt * 4 + kb) * 64 + lane) * 8);
; #pragma unroll
;     for (int vt = 0; vt < 4; ++vt)
; #pragma unroll
;         for (int kb = 0; kb < 4; ++kb) P.x[vt][kb] = *(const GAS bf16x8*)(p.sn + (size_t)((vt * 4 + kb) * 64 + lane) * 8);
; #pragma unroll
;     for (int vt = 0; vt < 8; ++vt) { P.ol[vt] = *(const GAS u64_t*)(p.oloc + (size_t)((vt * 4 + p.mt) * 64 + lane) * 4); P.gt8[vt] = *(const GAS u64_t*)(p.region + 24576 + t * 128 + 16 * vt + 4 * g); }
; }
; __device__ __forceinline__ void p4_run(int gw, int NGW, const bf16_t* HGR, const bf16_t* DNR, const bf16_t* OLH, const bf16_t* OLD, const bf16_t* BNB, const float* hg_nw, const float* dn_nw, bf16_t* OAB, int lane) {
;     const int r = lane & 15, g = lane >> 4;
;     P4Pre P; P4Ptr p = p4_ptrs(gw, HGR, DNR, OLH, OLD, BNB, hg_nw, dn_nw);
;     if (gw < 8192) p4_load_a(P, p, lane);
;     for (int it = gw; it < 8192; it += NGW) {
;         asm volatile("" ::: "memory");
;         f32x4 o[8]; float ss = 0.f; u64_t gcur[8];
; #pragma unroll
;         for (int vt = 0; vt < 8; ++vt) gcur[vt] = P.gt8[vt];
.LBB0_890:
	s_add_u32 s10, s60, 0xa004000
	s_addc_u32 s11, s61, 0
	s_add_u32 s8, s60, 0xe000000
	s_addc_u32 s9, s61, 0
	s_cmp_lt_i32 s56, 5
	s_cselect_b64 s[0:1], -1, 0
	s_cmp_gt_i32 s57, 4
	s_cselect_b64 s[4:5], -1, 0
	s_and_b64 s[0:1], s[0:1], s[4:5]
	s_andn2_b64 vcc, exec, s[0:1]
	s_cbranch_vccnz .LBB0_946
	s_and_b32 s4, s72, 56
	s_and_b32 s0, s73, 7
	s_or_b32 s4, s4, s0
	s_lshl_b32 s4, s4, 6
	s_lshr_b32 s0, s2, 6
	s_lshl_b32 s0, s0, 3
	s_add_i32 s4, s4, s0
	s_add_i32 s4, s4, s48
	s_cmpk_gt_i32 s4, 0x1fff
	s_cbranch_scc1 .LBB0_896
	s_waitcnt vmcnt(0)
	s_bfe_u32 s38, s66, 0x20006
	v_lshlrev_b32_e32 v210, 4, v234
	v_and_b32_e32 v211, 15, v234
	v_lshrrev_b32_e32 v212, 4, v234
	v_lshlrev_b32_e32 v213, 8, v211
	v_lshl_or_b32 v213, v212, 3, v213
	v_and_b32_e32 v214, 1, v212
	v_lshlrev_b32_e32 v214, 5, v214
	v_lshrrev_b32_e32 v215, 1, v212
	v_lshl_or_b32 v214, v215, 4, v214
	v_lshl_or_b32 v214, v211, 11, v214
	v_lshlrev_b32_e32 v215, 4, v212
	v_lshlrev_b32_e32 v216, 3, v234
	v_xor_b32_e32 v217, 16, v234
	v_lshlrev_b32_e32 v217, 2, v217
	v_xor_b32_e32 v218, 32, v234
	v_lshlrev_b32_e32 v218, 2, v218
	v_mov_b32_e32 v219, 0x358637bd
.Lp4n_item:
	s_bfe_u32 s36, s4, 0xa0002
	s_bfe_u32 s47, s4, 0x20002
	s_cmpk_lt_u32 s4, 0x1000
	s_cselect_b32 s6, s26, s62
	s_cselect_b32 s7, s27, s63
	s_lshl_b32 s3, s36, 16
	s_add_u32 s28, s6, s3
	s_addc_u32 s29, s7, 0
	s_add_u32 s40, s28, 0x4000
	s_addc_u32 s41, s29, 0
	s_lshl_b32 s3, s36, 15
	s_add_u32 s42, s64, s3
	s_addc_u32 s43, s65, 0
	s_cmpk_lt_u32 s4, 0x1000
	s_cselect_b32 s40, s40, s42
	s_cselect_b32 s41, s41, s43
	s_add_u32 s42, s60, 0xf000000
	s_addc_u32 s43, s61, 0
	s_cmpk_lt_u32 s4, 0x1000
	s_cselect_b32 s42, s8, s42
	s_cselect_b32 s43, s9, s43
	s_lshl_b32 s3, s36, 14
	s_add_u32 s42, s42, s3
	s_addc_u32 s43, s43, 0
	s_lshl_b32 s3, s38, 9
	s_add_u32 s42, s42, s3
	s_addc_u32 s43, s43, 0
	s_lshl_b32 s3, s47, 9
	s_add_u32 s44, s24, s3
	s_addc_u32 s45, s25, 0
	s_cmpk_lt_u32 s4, 0x1000
	s_cselect_b32 s44, s44, s30
	s_cselect_b32 s45, s45, s31
	s_lshl_b32 s3, s38, 12
	s_add_u32 s50, s28, s3
	s_addc_u32 s51, s29, 0
	s_add_u32 s18, s50, 0xc000
	s_addc_u32 s19, s51, 0
	s_lshr_b32 s3, s36, 2
	s_lshl_b32 s3, s3, 2
	s_or_b32 s3, s3, s38
	s_lshl_b32 s3, s3, 16
	s_add_u32 s68, s10, s3
	s_addc_u32 s69, s11, 0
	s_lshr_b32 s3, s4, 12
	s_lshl_b32 s3, s3, 10
	s_lshl_b32 s33, s47, 8
	s_or_b32 s3, s3, s33
	s_add_u32 s68, s68, s3
	s_addc_u32 s69, s69, 0
	global_load_dwordx4 v[2:5], v210, s[50:51]
	global_load_dwordx4 v[6:9], v210, s[50:51] offset:1024
	global_load_dwordx4 v[10:13], v210, s[50:51] offset:2048
	global_load_dwordx4 v[14:17], v210, s[50:51] offset:3072
	global_load_dwordx4 v[18:21], v210, s[40:41]
	global_load_dwordx4 v[22:25], v210, s[40:41] offset:1024
	global_load_dwordx4 v[26:29], v210, s[40:41] offset:2048
	global_load_dwordx4 v[30:33], v210, s[40:41] offset:3072
	s_add_u32 s40, s40, 0x1000
	s_addc_u32 s41, s41, 0
	global_load_dwordx4 v[34:37], v210, s[40:41]
	global_load_dwordx4 v[38:41], v210, s[40:41] offset:1024
	global_load_dwordx4 v[42:45], v210, s[40:41] offset:2048
	global_load_dwordx4 v[46:49], v210, s[40:41] offset:3072
	s_add_u32 s40, s40, 0x1000
	s_addc_u32 s41, s41, 0
	global_load_dwordx4 v[50:53], v210, s[40:41]
	global_load_dwordx4 v[54:57], v210, s[40:41] offset:1024
	global_load_dwordx4 v[58:61], v210, s[40:41] offset:2048
	global_load_dwordx4 v[62:65], v210, s[40:41] offset:3072
	s_add_u32 s40, s40, 0x1000
	s_addc_u32 s41, s41, 0
	global_load_dwordx4 v[66:69], v210, s[40:41]
	global_load_dwordx4 v[70:73], v210, s[40:41] offset:1024
	global_load_dwordx4 v[74:77], v210, s[40:41] offset:2048
	global_load_dwordx4 v[78:81], v210, s[40:41] offset:3072
	s_add_u32 s40, s40, 0x1000
	s_addc_u32 s41, s41, 0
	global_load_dwordx4 v[82:85], v210, s[40:41]
	global_load_dwordx4 v[86:89], v210, s[40:41] offset:1024
	global_load_dwordx4 v[90:93], v210, s[40:41] offset:2048
	global_load_dwordx4 v[94:97], v210, s[40:41] offset:3072
	s_add_u32 s40, s40, 0x1000
	s_addc_u32 s41, s41, 0
	global_load_dwordx4 v[98:101], v210, s[40:41]
	global_load_dwordx4 v[102:105], v210, s[40:41] offset:1024
	global_load_dwordx4 v[106:109], v210, s[40:41] offset:2048
	global_load_dwordx4 v[110:113], v210, s[40:41] offset:3072
	s_add_u32 s40, s40, 0x1000
	s_addc_u32 s41, s41, 0
	global_load_dwordx4 v[114:117], v210, s[40:41]
	global_load_dwordx4 v[118:121], v210, s[40:41] offset:1024
	global_load_dwordx4 v[122:125], v210, s[40:41] offset:2048
	global_load_dwordx4 v[126:129], v210, s[40:41] offset:3072
	s_add_u32 s40, s40, 0x1000
	s_addc_u32 s41, s41, 0
	global_load_dwordx4 v[130:133], v210, s[40:41]
	global_load_dwordx4 v[134:137], v210, s[40:41] offset:1024
	global_load_dwordx4 v[138:141], v210, s[40:41] offset:2048
	global_load_dwordx4 v[142:145], v210, s[40:41] offset:3072
	global_load_dwordx2 v[146:147], v216, s[42:43]
	global_load_dwordx2 v[148:149], v216, s[42:43] offset:2048
	s_add_u32 s42, s42, 0x1000
	s_addc_u32 s43, s43, 0
	global_load_dwordx2 v[150:151], v216, s[42:43]
	global_load_dwordx2 v[152:153], v216, s[42:43] offset:2048
	s_add_u32 s42, s42, 0x1000
	s_addc_u32 s43, s43, 0
	global_load_dwordx2 v[154:155], v216, s[42:43]
	global_load_dwordx2 v[156:157], v216, s[42:43] offset:2048
	s_add_u32 s42, s42, 0x1000
	s_addc_u32 s43, s43, 0
	global_load_dwordx2 v[158:159], v216, s[42:43]
	global_load_dwordx2 v[160:161], v216, s[42:43] offset:2048
	global_load_dwordx2 v[162:163], v213, s[18:19]
	global_load_dwordx2 v[164:165], v213, s[18:19] offset:32
	global_load_dwordx2 v[166:167], v213, s[18:19] offset:64
	global_load_dwordx2 v[168:169], v213, s[18:19] offset:96
	global_load_dwordx2 v[170:171], v213, s[18:19] offset:128
	global_load_dwordx2 v[172:173], v213, s[18:19] offset:160
	global_load_dwordx2 v[174:175], v213, s[18:19] offset:192
	global_load_dwordx2 v[176:177], v213, s[18:19] offset:224
	s_waitcnt vmcnt(8)
; #define GAS __attribute__((address_space(1)))
; #define MFMA16(a, b, c) __builtin_amdgcn_mfma_f32_16x16x32_bf16((a), (b), (c), 0, 0, 0)
; __device__ __forceinline__ void p4_run(int gw, int NGW, const bf16_t* HGR, const bf16_t* DNR, const bf16_t* OLH, const bf16_t* OLD, const bf16_t* BNB, const float* hg_nw, const float* dn_nw, bf16_t* OAB, int lane) {
;     ...
;         for (int vt = 0; vt < 8; ++vt) gcur[vt] = P.gt8[vt];
; #pragma unroll
;         for (int vt = 0; vt < 4; ++vt) { f32x4 acc = unpack4(P.ol[vt]);
; #pragma unroll
;             for (int kb = 0; kb < 4; ++kb) acc = MFMA16(P.x[vt][kb], P.ya[kb], acc);
;             o[vt] = acc; ss += (acc[0] * acc[0] + acc[1] * acc[1]) + (acc[2] * acc[2] + acc[3] * acc[3]); }
;         asm volatile("" ::: "memory");
; #pragma unroll
;         for (int vt = 0; vt < 4; ++vt)
; #pragma unroll
;             for (int kb = 0; kb < 4; ++kb) P.x[vt][kb] = *(const GAS bf16x8*)(p.sn + (size_t)(((vt + 4) * 4 + kb) * 64 + lane) * 8);
;         f32x4 w8[8];
; #pragma unroll
;         for (int vt = 0; vt < 8; ++vt) w8[vt] = *(const GAS f32x4*)(p.nw + 16 * vt + 4 * g);
;         asm volatile("" ::: "memory");
; #pragma unroll
;         for (int vt = 0; vt < 4; ++vt) { f32x4 acc = unpack4(P.ol[vt + 4]);
; #pragma unroll
;             for (int kb = 0; kb < 4; ++kb) acc = MFMA16(P.x[vt][kb], P.ya[kb], acc);
;             o[vt + 4] = acc; ss += (acc[0] * acc[0] + acc[1] * acc[1]) + (acc[2] * acc[2] + acc[3] * acc[3]); }
	v_lshlrev_b32_e32 v178, 16, v146
	v_and_b32_e32 v179, 0xffff0000, v146
	v_lshlrev_b32_e32 v180, 16, v147
	v_and_b32_e32 v181, 0xffff0000, v147
	v_lshlrev_b32_e32 v182, 16, v148
	v_and_b32_e32 v183, 0xffff0000, v148
	v_lshlrev_b32_e32 v184, 16, v149
	v_and_b32_e32 v185, 0xffff0000, v149
	v_lshlrev_b32_e32 v186, 16, v150
	v_and_b32_e32 v187, 0xffff0000, v150
	v_lshlrev_b32_e32 v188, 16, v151
	v_and_b32_e32 v189, 0xffff0000, v151
	v_lshlrev_b32_e32 v190, 16, v152
	v_and_b32_e32 v191, 0xffff0000, v152
	v_lshlrev_b32_e32 v192, 16, v153
	v_and_b32_e32 v193, 0xffff0000, v153
	v_lshlrev_b32_e32 v194, 16, v154
	v_and_b32_e32 v195, 0xffff0000, v154
	v_lshlrev_b32_e32 v196, 16, v155
	v_and_b32_e32 v197, 0xffff0000, v155
	v_lshlrev_b32_e32 v198, 16, v156
	v_and_b32_e32 v199, 0xffff0000, v156
	v_lshlrev_b32_e32 v200, 16, v157
	v_and_b32_e32 v201, 0xffff0000, v157
	v_lshlrev_b32_e32 v202, 16, v158
	v_and_b32_e32 v203, 0xffff0000, v158
	v_lshlrev_b32_e32 v204, 16, v159
	v_and_b32_e32 v205, 0xffff0000, v159
	v_lshlrev_b32_e32 v206, 16, v160
	v_and_b32_e32 v207, 0xffff0000, v160
	v_lshlrev_b32_e32 v208, 16, v161
	v_and_b32_e32 v209, 0xffff0000, v161
	s_nop 1
	v_mfma_f32_16x16x32_bf16 v[178:181], v[18:21], v[2:5], v[178:181]
	v_mfma_f32_16x16x32_bf16 v[182:185], v[34:37], v[2:5], v[182:185]
	v_mfma_f32_16x16x32_bf16 v[186:189], v[50:53], v[2:5], v[186:189]
	v_mfma_f32_16x16x32_bf16 v[190:193], v[66:69], v[2:5], v[190:193]
	v_mfma_f32_16x16x32_bf16 v[194:197], v[82:85], v[2:5], v[194:197]
	v_mfma_f32_16x16x32_bf16 v[198:201], v[98:101], v[2:5], v[198:201]
	v_mfma_f32_16x16x32_bf16 v[202:205], v[114:117], v[2:5], v[202:205]
	v_mfma_f32_16x16x32_bf16 v[206:209], v[130:133], v[2:5], v[206:209]
	global_load_dwordx4 v[18:21], v215, s[44:45]
	global_load_dwordx4 v[34:37], v215, s[44:45] offset:64
	global_load_dwordx4 v[50:53], v215, s[44:45] offset:128
	global_load_dwordx4 v[66:69], v215, s[44:45] offset:192
	global_load_dwordx4 v[82:85], v215, s[44:45] offset:256
	global_load_dwordx4 v[98:101], v215, s[44:45] offset:320
	global_load_dwordx4 v[114:117], v215, s[44:45] offset:384
	global_load_dwordx4 v[130:133], v215, s[44:45] offset:448
	v_mfma_f32_16x16x32_bf16 v[178:181], v[22:25], v[6:9], v[178:181]
	v_mfma_f32_16x16x32_bf16 v[182:185], v[38:41], v[6:9], v[182:185]
	v_mfma_f32_16x16x32_bf16 v[186:189], v[54:57], v[6:9], v[186:189]
	v_mfma_f32_16x16x32_bf16 v[190:193], v[70:73], v[6:9], v[190:193]
	v_mfma_f32_16x16x32_bf16 v[194:197], v[86:89], v[6:9], v[194:197]
	v_mfma_f32_16x16x32_bf16 v[198:201], v[102:105], v[6:9], v[198:201]
	v_mfma_f32_16x16x32_bf16 v[202:205], v[118:121], v[6:9], v[202:205]
	v_mfma_f32_16x16x32_bf16 v[206:209], v[134:137], v[6:9], v[206:209]
	v_mfma_f32_16x16x32_bf16 v[178:181], v[26:29], v[10:13], v[178:181]
	v_mfma_f32_16x16x32_bf16 v[182:185], v[42:45], v[10:13], v[182:185]
	v_mfma_f32_16x16x32_bf16 v[186:189], v[58:61], v[10:13], v[186:189]
	v_mfma_f32_16x16x32_bf16 v[190:193], v[74:77], v[10:13], v[190:193]
	v_mfma_f32_16x16x32_bf16 v[194:197], v[90:93], v[10:13], v[194:197]
	v_mfma_f32_16x16x32_bf16 v[198:201], v[106:109], v[10:13], v[198:201]
	v_mfma_f32_16x16x32_bf16 v[202:205], v[122:125], v[10:13], v[202:205]
	v_mfma_f32_16x16x32_bf16 v[206:209], v[138:141], v[10:13], v[206:209]
	v_mfma_f32_16x16x32_bf16 v[178:181], v[30:33], v[14:17], v[178:181]
	v_mfma_f32_16x16x32_bf16 v[182:185], v[46:49], v[14:17], v[182:185]
	v_mfma_f32_16x16x32_bf16 v[186:189], v[62:65], v[14:17], v[186:189]
	v_mfma_f32_16x16x32_bf16 v[190:193], v[78:81], v[14:17], v[190:193]
	v_mfma_f32_16x16x32_bf16 v[194:197], v[94:97], v[14:17], v[194:197]
	v_mfma_f32_16x16x32_bf16 v[198:201], v[110:113], v[14:17], v[198:201]
	v_mfma_f32_16x16x32_bf16 v[202:205], v[126:129], v[14:17], v[202:205]
	v_mfma_f32_16x16x32_bf16 v[206:209], v[142:145], v[14:17], v[206:209]
	s_nop 7
	s_nop 3
	v_mul_f32_e32 v149, v179, v179
	v_mul_f32_e32 v150, v181, v181
	v_fmac_f32_e32 v149, v178, v178
	v_fmac_f32_e32 v150, v180, v180
	v_add_f32_e32 v149, v149, v150
	v_mov_b32_e32 v148, v149
	v_mul_f32_e32 v149, v183, v183
	v_mul_f32_e32 v150, v185, v185
	v_fmac_f32_e32 v149, v182, v182
	v_fmac_f32_e32 v150, v184, v184
	v_add_f32_e32 v149, v149, v150
	v_add_f32_e32 v148, v148, v149
	v_mul_f32_e32 v149, v187, v187
	v_mul_f32_e32 v150, v189, v189
	v_fmac_f32_e32 v149, v186, v186
	v_fmac_f32_e32 v150, v188, v188
	v_add_f32_e32 v149, v149, v150
	v_add_f32_e32 v148, v148, v149
	v_mul_f32_e32 v149, v191, v191
	v_mul_f32_e32 v150, v193, v193
	v_fmac_f32_e32 v149, v190, v190
	v_fmac_f32_e32 v150, v192, v192
	v_add_f32_e32 v149, v149, v150
	v_add_f32_e32 v148, v148, v149
	v_mul_f32_e32 v149, v195, v195
	v_mul_f32_e32 v150, v197, v197
	v_fmac_f32_e32 v149, v194, v194
	v_fmac_f32_e32 v150, v196, v196
	v_add_f32_e32 v149, v149, v150
	v_add_f32_e32 v148, v148, v149
	v_mul_f32_e32 v149, v199, v199
	v_mul_f32_e32 v150, v201, v201
	v_fmac_f32_e32 v149, v198, v198
	v_fmac_f32_e32 v150, v200, v200
	v_add_f32_e32 v149, v149, v150
	v_add_f32_e32 v148, v148, v149
	v_mul_f32_e32 v149, v203, v203
	v_mul_f32_e32 v150, v205, v205
	v_fmac_f32_e32 v149, v202, v202
	v_fmac_f32_e32 v150, v204, v204
	v_add_f32_e32 v149, v149, v150
	v_add_f32_e32 v148, v148, v149
	v_mul_f32_e32 v149, v207, v207
	v_mul_f32_e32 v150, v209, v209
	v_fmac_f32_e32 v149, v206, v206
	v_fmac_f32_e32 v150, v208, v208
	v_add_f32_e32 v149, v149, v150
	v_add_f32_e32 v148, v148, v149
	ds_bpermute_b32 v149, v217, v148
	s_waitcnt lgkmcnt(0)
; #define GAS __attribute__((address_space(1)))
; __device__ __forceinline__ u64_t pack4(const f32x4 v) { return (u64_t)pk2(v[0], v[1]) | ((u64_t)pk2(v[2], v[3]) << 32); }
; __device__ __forceinline__ void p4_run(int gw, int NGW, const bf16_t* HGR, const bf16_t* DNR, const bf16_t* OLH, const bf16_t* OLD, const bf16_t* BNB, const float* hg_nw, const float* dn_nw, bf16_t* OAB, int lane) {
;     ...
;         const int t = 16 * p.mt + r;
;         bf16_t* orow2 = OAB + (size_t)(p.rb * 4 + p.mt) * 32768 + r * 1024 + p.br * 512 + p.h * 128 + 16 * (g & 1) + 8 * (g >> 1);
;         asm volatile("" :: "v"(o[4][0]), "v"(o[5][0]), "v"(o[6][0]), "v"(o[7][0]) : "memory");
;         if (it + NGW < 8192) { p = p4_ptrs(it + NGW, HGR, DNR, OLH, OLD, BNB, hg_nw, dn_nw); p4_load_a(P, p, lane); }
;         asm volatile("" ::: "memory");
;         ss += __shfl_xor(ss, 16); ss += __shfl_xor(ss, 32);
;         const float rstd = rsqrtf(ss * (1.f / 128.f) + RMS_EPS);
; #pragma unroll
;         for (int p2 = 0; p2 < 4; ++p2) {
;             const u64_t X = pack4(o[2 * p2] * rstd * w8[2 * p2] * unpack4(gcur[2 * p2])), Y = pack4(o[2 * p2 + 1] * rstd * w8[2 * p2 + 1] * unpack4(gcur[2 * p2 + 1]));
;             const auto lo = __builtin_amdgcn_permlane16_swap((unsigned)X, (unsigned)Y, false, false), hi = __builtin_amdgcn_permlane16_swap((unsigned)(X >> 32), (unsigned)(Y >> 32), false, false);
;             *(GAS v4u*)(orow2 + 32 * p2) = (v4u){lo[0], hi[0], lo[1], hi[1]}; }
;     }
	v_add_f32_e32 v148, v148, v149
	ds_bpermute_b32 v149, v218, v148
	s_waitcnt lgkmcnt(0)
	v_add_f32_e32 v148, v148, v149
	v_fmamk_f32 v148, v148, 0x3c000000, v219
	v_rsq_f32_e32 v146, v148
	v_mov_b32_e32 v147, 0
	s_waitcnt vmcnt(0)
	v_pk_mul_f32 v[178:179], v[178:179], v[146:147] op_sel_hi:[1,0]
	v_pk_mul_f32 v[180:181], v[180:181], v[146:147] op_sel_hi:[1,0]
	v_lshlrev_b32_e32 v22, 16, v162
	v_and_b32_e32 v23, 0xffff0000, v162
	v_lshlrev_b32_e32 v24, 16, v163
	v_and_b32_e32 v25, 0xffff0000, v163
	v_pk_mul_f32 v[178:179], v[18:19], v[178:179]
	v_pk_mul_f32 v[180:181], v[20:21], v[180:181]
	v_pk_mul_f32 v[178:179], v[178:179], v[22:23]
	v_pk_mul_f32 v[180:181], v[180:181], v[24:25]
	v_cvt_pk_bf16_f32 v26, v178, v179
	v_cvt_pk_bf16_f32 v27, v180, v181
	v_pk_mul_f32 v[182:183], v[182:183], v[146:147] op_sel_hi:[1,0]
	v_pk_mul_f32 v[184:185], v[184:185], v[146:147] op_sel_hi:[1,0]
	v_lshlrev_b32_e32 v38, 16, v164
	v_and_b32_e32 v39, 0xffff0000, v164
	v_lshlrev_b32_e32 v40, 16, v165
	v_and_b32_e32 v41, 0xffff0000, v165
	v_pk_mul_f32 v[182:183], v[34:35], v[182:183]
	v_pk_mul_f32 v[184:185], v[36:37], v[184:185]
	v_pk_mul_f32 v[182:183], v[182:183], v[38:39]
	v_pk_mul_f32 v[184:185], v[184:185], v[40:41]
	v_cvt_pk_bf16_f32 v28, v182, v183
	v_cvt_pk_bf16_f32 v29, v184, v185
	s_nop 1
	v_permlane16_swap_b32_e32 v26, v28
	v_permlane16_swap_b32_e32 v27, v29
	global_store_dwordx4 v214, v[26:29], s[68:69]
	v_pk_mul_f32 v[186:187], v[186:187], v[146:147] op_sel_hi:[1,0]
	v_pk_mul_f32 v[188:189], v[188:189], v[146:147] op_sel_hi:[1,0]
	v_lshlrev_b32_e32 v54, 16, v166
	v_and_b32_e32 v55, 0xffff0000, v166
	v_lshlrev_b32_e32 v56, 16, v167
	v_and_b32_e32 v57, 0xffff0000, v167
	v_pk_mul_f32 v[186:187], v[50:51], v[186:187]
	v_pk_mul_f32 v[188:189], v[52:53], v[188:189]
	v_pk_mul_f32 v[186:187], v[186:187], v[54:55]
	v_pk_mul_f32 v[188:189], v[188:189], v[56:57]
	v_cvt_pk_bf16_f32 v58, v186, v187
	v_cvt_pk_bf16_f32 v59, v188, v189
	v_pk_mul_f32 v[190:191], v[190:191], v[146:147] op_sel_hi:[1,0]
	v_pk_mul_f32 v[192:193], v[192:193], v[146:147] op_sel_hi:[1,0]
	v_lshlrev_b32_e32 v70, 16, v168
	v_and_b32_e32 v71, 0xffff0000, v168
	v_lshlrev_b32_e32 v72, 16, v169
	v_and_b32_e32 v73, 0xffff0000, v169
	v_pk_mul_f32 v[190:191], v[66:67], v[190:191]
	v_pk_mul_f32 v[192:193], v[68:69], v[192:193]
	v_pk_mul_f32 v[190:191], v[190:191], v[70:71]
	v_pk_mul_f32 v[192:193], v[192:193], v[72:73]
	v_cvt_pk_bf16_f32 v60, v190, v191
	v_cvt_pk_bf16_f32 v61, v192, v193
	s_nop 1
	v_permlane16_swap_b32_e32 v58, v60
	v_permlane16_swap_b32_e32 v59, v61
	global_store_dwordx4 v214, v[58:61], s[68:69] offset:64
	v_pk_mul_f32 v[194:195], v[194:195], v[146:147] op_sel_hi:[1,0]
	v_pk_mul_f32 v[196:197], v[196:197], v[146:147] op_sel_hi:[1,0]
	v_lshlrev_b32_e32 v86, 16, v170
	v_and_b32_e32 v87, 0xffff0000, v170
	v_lshlrev_b32_e32 v88, 16, v171
	v_and_b32_e32 v89, 0xffff0000, v171
	v_pk_mul_f32 v[194:195], v[82:83], v[194:195]
	v_pk_mul_f32 v[196:197], v[84:85], v[196:197]
	v_pk_mul_f32 v[194:195], v[194:195], v[86:87]
	v_pk_mul_f32 v[196:197], v[196:197], v[88:89]
	v_cvt_pk_bf16_f32 v90, v194, v195
	v_cvt_pk_bf16_f32 v91, v196, v197
	v_pk_mul_f32 v[198:199], v[198:199], v[146:147] op_sel_hi:[1,0]
	v_pk_mul_f32 v[200:201], v[200:201], v[146:147] op_sel_hi:[1,0]
	v_lshlrev_b32_e32 v102, 16, v172
	v_and_b32_e32 v103, 0xffff0000, v172
	v_lshlrev_b32_e32 v104, 16, v173
	v_and_b32_e32 v105, 0xffff0000, v173
	v_pk_mul_f32 v[198:199], v[98:99], v[198:199]
	v_pk_mul_f32 v[200:201], v[100:101], v[200:201]
	v_pk_mul_f32 v[198:199], v[198:199], v[102:103]
	v_pk_mul_f32 v[200:201], v[200:201], v[104:105]
	v_cvt_pk_bf16_f32 v92, v198, v199
	v_cvt_pk_bf16_f32 v93, v200, v201
	s_nop 1
	v_permlane16_swap_b32_e32 v90, v92
	v_permlane16_swap_b32_e32 v91, v93
	global_store_dwordx4 v214, v[90:93], s[68:69] offset:128
	v_pk_mul_f32 v[202:203], v[202:203], v[146:147] op_sel_hi:[1,0]
	v_pk_mul_f32 v[204:205], v[204:205], v[146:147] op_sel_hi:[1,0]
	v_lshlrev_b32_e32 v118, 16, v174
	v_and_b32_e32 v119, 0xffff0000, v174
	v_lshlrev_b32_e32 v120, 16, v175
	v_and_b32_e32 v121, 0xffff0000, v175
	v_pk_mul_f32 v[202:203], v[114:115], v[202:203]
	v_pk_mul_f32 v[204:205], v[116:117], v[204:205]
	v_pk_mul_f32 v[202:203], v[202:203], v[118:119]
	v_pk_mul_f32 v[204:205], v[204:205], v[120:121]
	v_cvt_pk_bf16_f32 v122, v202, v203
	v_cvt_pk_bf16_f32 v123, v204, v205
	v_pk_mul_f32 v[206:207], v[206:207], v[146:147] op_sel_hi:[1,0]
	v_pk_mul_f32 v[208:209], v[208:209], v[146:147] op_sel_hi:[1,0]
	v_lshlrev_b32_e32 v134, 16, v176
	v_and_b32_e32 v135, 0xffff0000, v176
	v_lshlrev_b32_e32 v136, 16, v177
	v_and_b32_e32 v137, 0xffff0000, v177
	v_pk_mul_f32 v[206:207], v[130:131], v[206:207]
	v_pk_mul_f32 v[208:209], v[132:133], v[208:209]
	v_pk_mul_f32 v[206:207], v[206:207], v[134:135]
	v_pk_mul_f32 v[208:209], v[208:209], v[136:137]
	v_cvt_pk_bf16_f32 v124, v206, v207
	v_cvt_pk_bf16_f32 v125, v208, v209
	s_nop 1
	v_permlane16_swap_b32_e32 v122, v124
	v_permlane16_swap_b32_e32 v123, v125
	global_store_dwordx4 v214, v[122:125], s[68:69] offset:192
	s_bitcmp1_b32 s4, 5
	s_cselect_b32 s35, 0xfe0, 32
	s_add_i32 s4, s4, s35
	s_cmpk_gt_i32 s4, 0x1fff
	s_cbranch_scc0 .Lp4n_item
